# grid-barrier poll sleep 12 (was 20)
# speedup vs baseline: 1.0067x; 1.0067x over previous
.LBB0_37:
	s_sleep 12
	global_load_dword v1, v0, s[8:9] sc1
	s_waitcnt vmcnt(0)
	v_cmp_gt_u32_e32 vcc, s2, v1
	s_cbranch_vccnz .LBB0_37

.LBB0_113:
	s_sleep 12
	global_load_dword v1, v0, s[10:11] sc1
	s_waitcnt vmcnt(0)
	v_cmp_gt_u32_e32 vcc, s2, v1
	s_cbranch_vccnz .LBB0_113

.LBB0_151:
	s_sleep 12
	global_load_dword v1, v0, s[6:7] sc1
	s_waitcnt vmcnt(0)
	v_cmp_gt_u32_e32 vcc, s2, v1
	s_cbranch_vccnz .LBB0_151

.LBB0_613:
	s_sleep 12
	global_load_dword v1, v0, s[10:11] sc1
	s_waitcnt vmcnt(0)
	v_cmp_gt_u32_e32 vcc, s3, v1
	s_cbranch_vccnz .LBB0_613

.Lfb_poll:
	global_load_dword v1, v0, s[10:11] offset:512 sc1
	s_waitcnt vmcnt(0)
	v_cmp_gt_u32_e32 vcc, 8, v1
	s_cbranch_vccz .Lfb_done
	s_sleep 12
	s_branch .Lfb_poll

.LBB0_702:
	s_sleep 12
	global_load_dword v1, v0, s[10:11] sc1
	s_waitcnt vmcnt(0)
	v_cmp_gt_u32_e32 vcc, s7, v1
	s_cbranch_vccnz .LBB0_702
